# three GEMM-to-GEMM seams (branch->w_o, w_o->mlp_in, mlp_in->mlp_out) use the XCD-local half of the hierarchical barrier: producers and consumers of a row panel share an XCD
# speedup vs baseline: 1.0114x; 1.0072x over previous
.LBB0_1174:
	s_andn2_saveexec_b64 s[4:5], s[4:5]
	s_cbranch_execz .LBB0_1190
	s_branch .Lxcd_local_b
	v_readlane_b32 s4, v254, 61
	buffer_wbl2 sc1
	s_waitcnt lgkmcnt(0)
	s_waitcnt vmcnt(0)
	v_readlane_b32 s5, v254, 62
	v_mov_b32_e32 v0, 1
	v_sub_u32_e32 v4, 0, v2
	s_mov_b64 s[18:19], -1
	s_nop 1
	global_atomic_add v3, v1, v0, s[4:5] sc0
	v_cvt_f32_u32_e32 v0, v2
	v_readlane_b32 s4, v254, 63
	v_readlane_b32 s5, v255, 0
	v_rcp_iflag_f32_e32 v0, v0
	s_nop 0
	v_mul_f32_e32 v0, 0x4f7ffffe, v0
	v_cvt_u32_f32_e32 v0, v0
	v_mul_lo_u32 v4, v4, v0
	v_mul_hi_u32 v4, v0, v4
	v_add_u32_e32 v0, v0, v4
	s_waitcnt vmcnt(0)
	v_mul_hi_u32 v0, v3, v0
	v_mul_lo_u32 v4, v0, v2
	v_sub_u32_e32 v4, v3, v4
	v_cmp_ge_u32_e32 vcc, v4, v2
	v_add_u32_e32 v5, 1, v0
	v_add_u32_e32 v3, 1, v3
	v_cndmask_b32_e32 v0, v0, v5, vcc
	v_sub_u32_e32 v5, v4, v2
	v_cndmask_b32_e32 v4, v4, v5, vcc
	v_cmp_ge_u32_e32 vcc, v4, v2
	v_add_u32_e32 v4, 1, v0
	s_nop 0
	v_cndmask_b32_e32 v0, v0, v4, vcc
	v_mul_lo_u32 v4, v2, v0
	v_add_u32_e32 v2, v4, v2
	v_cmp_ne_u32_e32 vcc, v3, v2
	v_mov_b64_e32 v[2:3], s[4:5]
	s_and_saveexec_b64 s[4:5], vcc
	s_cbranch_execz .LBB0_1187
	v_readlane_b32 s8, v254, 63
	v_readlane_b32 s9, v255, 0
	s_mov_b64 s[28:29], 0
	s_nop 3
	global_load_dword v2, v1, s[8:9] sc1
	s_waitcnt vmcnt(0)
	v_cmp_eq_u32_e32 vcc, v2, v0
	s_and_saveexec_b64 s[18:19], vcc
	s_cbranch_execz .LBB0_1186
	s_mov_b32 s7, 1
	s_mov_b64 s[30:31], 0
	s_branch .LBB0_1179

.Lxcd_local_b:
	v_readlane_b32 s4, v254, 59
	v_readlane_b32 s5, v254, 60
	v_mov_b32_e32 v0, 1
	s_waitcnt vmcnt(0)
	buffer_inv sc1
	s_nop 1
	global_atomic_add v1, v0, s[4:5]
	s_waitcnt vmcnt(0)

.LBB0_1279:
	s_andn2_saveexec_b64 s[4:5], s[4:5]
	s_cbranch_execz .LBB0_1295
	s_branch .Lxcd_local_a
	v_readlane_b32 s4, v254, 61
	buffer_wbl2 sc1
	s_waitcnt lgkmcnt(0)
	s_waitcnt vmcnt(0)
	v_readlane_b32 s5, v254, 62
	v_mov_b32_e32 v0, 1
	v_sub_u32_e32 v4, 0, v2
	s_mov_b64 s[18:19], -1
	s_nop 1
	global_atomic_add v3, v1, v0, s[4:5] sc0
	v_cvt_f32_u32_e32 v0, v2
	v_readlane_b32 s4, v254, 63
	v_readlane_b32 s5, v255, 0
	v_rcp_iflag_f32_e32 v0, v0
	s_nop 0
	v_mul_f32_e32 v0, 0x4f7ffffe, v0
	v_cvt_u32_f32_e32 v0, v0
	v_mul_lo_u32 v4, v4, v0
	v_mul_hi_u32 v4, v0, v4
	v_add_u32_e32 v0, v0, v4
	s_waitcnt vmcnt(0)
	v_mul_hi_u32 v0, v3, v0
	v_mul_lo_u32 v4, v0, v2
	v_sub_u32_e32 v4, v3, v4
	v_cmp_ge_u32_e32 vcc, v4, v2
	v_add_u32_e32 v5, 1, v0
	v_add_u32_e32 v3, 1, v3
	v_cndmask_b32_e32 v0, v0, v5, vcc
	v_sub_u32_e32 v5, v4, v2
	v_cndmask_b32_e32 v4, v4, v5, vcc
	v_cmp_ge_u32_e32 vcc, v4, v2
	v_add_u32_e32 v4, 1, v0
	s_nop 0
	v_cndmask_b32_e32 v0, v0, v4, vcc
	v_mul_lo_u32 v4, v2, v0
	v_add_u32_e32 v2, v4, v2
	v_cmp_ne_u32_e32 vcc, v3, v2
	v_mov_b64_e32 v[2:3], s[4:5]
	s_and_saveexec_b64 s[4:5], vcc
	s_cbranch_execz .LBB0_1292
	v_readlane_b32 s8, v254, 63
	v_readlane_b32 s9, v255, 0
	s_mov_b64 s[28:29], 0
	s_nop 3
	global_load_dword v2, v1, s[8:9] sc1
	s_waitcnt vmcnt(0)
	v_cmp_eq_u32_e32 vcc, v2, v0
	s_and_saveexec_b64 s[18:19], vcc
	s_cbranch_execz .LBB0_1291
	s_mov_b32 s1, 1
	s_mov_b64 s[30:31], 0
	s_branch .LBB0_1284
